# P0 weight-conversion items assigned to waves in mirrored order so the waves with two adaLN GEMV items get one fewer transpose item
# baseline (speedup 1.0000x reference)
.LBB0_24:
	s_lshl_b32 s58, s76, 3
	s_sub_i32 s38, s58, s38
	s_add_i32 s38, s38, -1
	s_cmpk_lt_i32 s38, 0x3200
	s_barrier
	s_cbranch_scc0 .LBB0_62
	s_add_u32 s8, s6, 0x2c00000
	s_addc_u32 s9, s7, 0
	s_ashr_i32 s14, s38, 10
	s_ashr_i32 s15, s14, 31
	s_lshl_b64 s[12:13], s[14:15], 24
	s_add_u32 s10, s6, 0x1f400000
	s_addc_u32 s11, s7, 0
	s_and_b32 s47, s38, 0x3ff
	s_add_u32 s16, s27, s12
	s_addc_u32 s17, s28, s13
	s_add_u32 s39, s6, 0x2800000
	s_addc_u32 s40, s7, 0
	s_add_u32 s42, s6, 0xa000000
	s_addc_u32 s43, s7, 0
	s_add_u32 s44, s6, 0x9000000
	s_addc_u32 s45, s7, 0
	s_add_i32 s12, s14, -2
	s_cmp_lt_i32 s14, 2
	s_cselect_b32 s15, s15, 0
	s_cselect_b32 s14, s14, s12
	s_mov_b32 s46, 0x7000000
	s_cselect_b32 s12, s46, 0x800000
	s_lshl_b64 s[14:15], s[14:15], 23
	s_add_u32 s14, s6, s14
	s_addc_u32 s15, s7, s15
	s_add_u32 s18, s14, s12
	s_addc_u32 s19, s15, 0
	s_mov_b32 s13, 0
	s_movk_i32 s48, 0x1000
	s_cmpk_lt_i32 s38, 0x1000
	s_mov_b64 s[14:15], 0x400
	s_cbranch_scc1 .LBB0_31
	s_add_i32 s16, s38, 0xfffff000
	s_and_b32 s12, s16, 0xfffffc00
	s_lshl_b64 s[14:15], s[12:13], 14
	s_add_u32 s14, s29, s14
	s_addc_u32 s15, s30, s15
	s_lshr_b32 s12, s16, 10
	s_cmpk_lt_u32 s16, 0x800
	s_cselect_b64 s[16:17], -1, 0
	s_add_i32 s18, s12, -2
	s_and_b64 s[16:17], s[16:17], exec
	s_cselect_b32 s12, s12, s18
	s_brev_b32 s16, 16
	s_cselect_b32 s18, s16, 0x1800000
	s_lshl_b64 s[16:17], s[12:13], 23
	s_add_u32 s12, s6, s16
	s_addc_u32 s17, s7, s17
	s_add_u32 s16, s12, s18
	s_addc_u32 s17, s17, 0
	s_cmpk_lt_u32 s38, 0x2000
	s_cbranch_scc1 .LBB0_32
	s_and_b32 s12, s38, 0x3c00
	s_add_i32 s14, s12, 0xffffe000
	s_mov_b32 s15, 0
	s_lshl_b64 s[16:17], s[14:15], 14
	s_add_u32 s16, s31, s16
	s_addc_u32 s17, s33, s17
	s_lshl_b64 s[18:19], s[14:15], 13
	s_add_u32 s18, s44, s18
	s_addc_u32 s19, s45, s19
	s_cmpk_lt_u32 s38, 0x2800
	s_cbranch_scc1 .LBB0_34
	s_add_i32 s12, s38, 0xffffd800
	s_lshr_b32 s14, s12, 9
	s_lshl_b64 s[16:17], s[14:15], 23
	s_add_u32 s16, s34, s16
	s_addc_u32 s17, s35, s17
	s_lshl_b64 s[14:15], s[14:15], 22
	s_add_u32 s14, s42, s14
	s_addc_u32 s15, s43, s15
	s_cmpk_lt_u32 s38, 0x2c00
	s_cbranch_scc1 .LBB0_591
	s_cmpk_lt_u32 s38, 0x2e00
	s_cbranch_scc1 .LBB0_592
	s_add_i32 s12, s38, 0xffffd200
	s_mov_b32 s15, 0
	s_lshr_b32 s14, s12, 8
	v_mov_b32_e32 v2, 0x3000
	s_and_b32 s47, s38, 0xff
	s_lshl_b64 s[16:17], s[14:15], 22
	s_add_u32 s12, s36, s16
	v_sub_co_u32_e32 v2, vcc, s38, v2
	s_addc_u32 s16, s37, s17
	v_lshrrev_b32_e32 v2, 8, v2
	v_mov_b32_e32 v3, 0
	s_lshl_b64 s[14:15], s[14:15], 21
	v_lshlrev_b64 v[4:5], 22, v[2:3]
	v_lshlrev_b64 v[2:3], 21, v[2:3]
	s_add_u32 s14, s39, s14
	v_lshl_add_u64 v[4:5], s[4:5], 0, v[4:5]
	v_lshl_add_u64 v[6:7], s[8:9], 0, v[2:3]
	s_addc_u32 s15, s40, s15
	v_mov_b32_e32 v2, s12
	v_cndmask_b32_e32 v2, v4, v2, vcc
	v_mov_b32_e32 v4, s15
	v_mov_b32_e32 v8, s16
	v_cndmask_b32_e32 v131, v7, v4, vcc
	v_mov_b32_e32 v4, s14
	v_cndmask_b32_e32 v3, v5, v8, vcc
	v_cndmask_b32_e32 v130, v6, v4, vcc
	s_movk_i32 s48, 0x400
	s_branch .LBB0_35
